# combined: MFMA K-halves back to back + snake, redundant waits dropped, saddr LDS-DMA, attention fast PV
# speedup vs baseline: 1.0146x; 1.0065x over previous
.LBB0_120:
	s_add_u32 s28, s40, 0xfff80080
	s_addc_u32 s29, s41, -1
	s_add_i32 s54, 0, 0x10000
	s_cmp_eq_u32 s53, 28
	s_cselect_b32 s29, s23, s29
	s_cselect_b32 s28, s22, s28
	s_cselect_b32 s43, s21, s52
	s_cselect_b32 s42, s50, s51
	s_add_i32 s56, 0, 0x14000
	v_add_u32_e32 v142, s54, v212
	v_add_u32_e32 v158, s56, v212
	ds_read_b128 v[130:133], v142
	ds_read_b128 v[134:137], v142 offset:1024
	ds_read_b128 v[138:141], v142 offset:2048
	ds_read_b128 v[142:145], v142 offset:3072
	ds_read_b128 v[146:149], v158
	ds_read_b128 v[150:153], v158 offset:1024
	ds_read_b128 v[154:157], v158 offset:2048
	ds_read_b128 v[158:161], v158 offset:3072
	s_add_i32 m0, s24, 0xc000
	ds_read_b128 v[162:165], v213
	ds_read_b128 v[166:169], v213 offset:1024
	ds_read_b128 v[170:173], v213 offset:2048
	ds_read_b128 v[174:177], v213 offset:3072
	ds_read_b128 v[188:191], v213 offset:4096
	ds_read_b128 v[192:195], v213 offset:5120
	ds_read_b128 v[196:199], v213 offset:6144
	ds_read_b128 v[200:203], v213 offset:7168
	global_load_lds_dwordx4 v184, s[40:41]
	s_add_i32 m0, s24, 0xe000
	s_nop 0
	global_load_lds_dwordx4 v186, s[40:41]
	s_waitcnt vmcnt(8)
	s_waitcnt lgkmcnt(0)
	s_barrier
	s_setprio 1
	v_mfma_f32_16x16x32_bf16 v[126:129], v[130:133], v[162:165], v[126:129]
	v_mfma_f32_16x16x32_bf16 v[126:129], v[134:137], v[166:169], v[126:129]
	v_mfma_f32_16x16x32_bf16 v[122:125], v[142:145], v[166:169], v[122:125]
	v_mfma_f32_16x16x32_bf16 v[122:125], v[138:141], v[162:165], v[122:125]
	v_mfma_f32_16x16x32_bf16 v[106:109], v[138:141], v[170:173], v[106:109]
	v_mfma_f32_16x16x32_bf16 v[106:109], v[142:145], v[174:177], v[106:109]
	v_mfma_f32_16x16x32_bf16 v[110:113], v[134:137], v[174:177], v[110:113]
	v_mfma_f32_16x16x32_bf16 v[110:113], v[130:133], v[170:173], v[110:113]
	v_mfma_f32_16x16x32_bf16 v[94:97], v[130:133], v[188:191], v[94:97]
	v_mfma_f32_16x16x32_bf16 v[94:97], v[134:137], v[192:195], v[94:97]
	v_mfma_f32_16x16x32_bf16 v[90:93], v[142:145], v[192:195], v[90:93]
	v_mfma_f32_16x16x32_bf16 v[90:93], v[138:141], v[188:191], v[90:93]
	v_mfma_f32_16x16x32_bf16 v[74:77], v[138:141], v[196:199], v[74:77]
	v_mfma_f32_16x16x32_bf16 v[74:77], v[142:145], v[200:203], v[74:77]
	v_mfma_f32_16x16x32_bf16 v[78:81], v[134:137], v[200:203], v[78:81]
	v_mfma_f32_16x16x32_bf16 v[78:81], v[130:133], v[196:199], v[78:81]
	v_mfma_f32_16x16x32_bf16 v[118:121], v[146:149], v[162:165], v[118:121]
	v_mfma_f32_16x16x32_bf16 v[118:121], v[150:153], v[166:169], v[118:121]
	v_mfma_f32_16x16x32_bf16 v[114:117], v[158:161], v[166:169], v[114:117]
	v_mfma_f32_16x16x32_bf16 v[114:117], v[154:157], v[162:165], v[114:117]
	v_mfma_f32_16x16x32_bf16 v[98:101], v[154:157], v[170:173], v[98:101]
	v_mfma_f32_16x16x32_bf16 v[98:101], v[158:161], v[174:177], v[98:101]
	v_mfma_f32_16x16x32_bf16 v[102:105], v[150:153], v[174:177], v[102:105]
	v_mfma_f32_16x16x32_bf16 v[102:105], v[146:149], v[170:173], v[102:105]
	v_mfma_f32_16x16x32_bf16 v[86:89], v[146:149], v[188:191], v[86:89]
	v_mfma_f32_16x16x32_bf16 v[86:89], v[150:153], v[192:195], v[86:89]
	v_mfma_f32_16x16x32_bf16 v[82:85], v[158:161], v[192:195], v[82:85]
	v_mfma_f32_16x16x32_bf16 v[82:85], v[154:157], v[188:191], v[82:85]
	v_mfma_f32_16x16x32_bf16 v[66:69], v[154:157], v[196:199], v[66:69]
	v_mfma_f32_16x16x32_bf16 v[66:69], v[158:161], v[200:203], v[66:69]
	v_mfma_f32_16x16x32_bf16 v[70:73], v[150:153], v[200:203], v[70:73]
	v_mfma_f32_16x16x32_bf16 v[70:73], v[146:149], v[196:199], v[70:73]
	s_setprio 0
	s_barrier
	s_add_i32 s54, s54, s1
	v_lshl_add_u64 v[204:205], s[42:43], 0, v[32:33]
	s_mov_b32 m0, s54
	ds_read_b128 v[162:165], v213 offset:16384
	ds_read_b128 v[166:169], v213 offset:17408
	ds_read_b128 v[170:173], v213 offset:18432
	ds_read_b128 v[174:177], v213 offset:19456
	ds_read_b128 v[188:191], v213 offset:20480
	ds_read_b128 v[192:195], v213 offset:21504
	ds_read_b128 v[196:199], v213 offset:22528
	ds_read_b128 v[200:203], v213 offset:23552
	global_load_lds_dwordx4 v[204:205], off
	s_add_i32 m0, s54, 0x2000
	s_add_u32 s54, s42, 0x80000
	v_lshl_add_u64 v[206:207], s[42:43], 0, v[182:183]
	s_addc_u32 s55, s43, 0
	s_add_i32 s56, s56, s1
	global_load_lds_dwordx4 v[206:207], off
	s_mov_b32 m0, s56
	v_lshl_add_u64 v[214:215], s[28:29], 0, v[180:181]
	global_load_lds_dwordx4 v32, s[54:55]
	s_add_i32 m0, s56, 0x2000
	s_nop 0
	global_load_lds_dwordx4 v182, s[54:55]
	v_lshl_add_u64 v[208:209], s[28:29], 0, v[178:179]
	s_mov_b32 m0, s24
	s_nop 0
	global_load_lds_dwordx4 v[208:209], off
	s_mov_b32 m0, s25
	s_nop 0
	global_load_lds_dwordx4 v[214:215], off
	s_waitcnt vmcnt(8)
	s_waitcnt lgkmcnt(0)
	s_barrier
	s_setprio 1
	v_mfma_f32_16x16x32_bf16 v[62:65], v[130:133], v[162:165], v[62:65]
	v_mfma_f32_16x16x32_bf16 v[62:65], v[134:137], v[166:169], v[62:65]
	v_mfma_f32_16x16x32_bf16 v[58:61], v[142:145], v[166:169], v[58:61]
	v_mfma_f32_16x16x32_bf16 v[58:61], v[138:141], v[162:165], v[58:61]
	v_mfma_f32_16x16x32_bf16 v[42:45], v[138:141], v[170:173], v[42:45]
	v_mfma_f32_16x16x32_bf16 v[42:45], v[142:145], v[174:177], v[42:45]
	v_mfma_f32_16x16x32_bf16 v[46:49], v[134:137], v[174:177], v[46:49]
	v_mfma_f32_16x16x32_bf16 v[46:49], v[130:133], v[170:173], v[46:49]
	v_mfma_f32_16x16x32_bf16 v[28:31], v[130:133], v[188:191], v[28:31]
	v_mfma_f32_16x16x32_bf16 v[28:31], v[134:137], v[192:195], v[28:31]
	v_mfma_f32_16x16x32_bf16 v[24:27], v[142:145], v[192:195], v[24:27]
	v_mfma_f32_16x16x32_bf16 v[24:27], v[138:141], v[188:191], v[24:27]
	v_mfma_f32_16x16x32_bf16 v[8:11], v[138:141], v[196:199], v[8:11]
	v_mfma_f32_16x16x32_bf16 v[8:11], v[142:145], v[200:203], v[8:11]
	v_mfma_f32_16x16x32_bf16 v[12:15], v[134:137], v[200:203], v[12:15]
	v_mfma_f32_16x16x32_bf16 v[12:15], v[130:133], v[196:199], v[12:15]
	v_mfma_f32_16x16x32_bf16 v[54:57], v[146:149], v[162:165], v[54:57]
	v_mfma_f32_16x16x32_bf16 v[54:57], v[150:153], v[166:169], v[54:57]
	v_mfma_f32_16x16x32_bf16 v[50:53], v[158:161], v[166:169], v[50:53]
	v_mfma_f32_16x16x32_bf16 v[50:53], v[154:157], v[162:165], v[50:53]
	v_mfma_f32_16x16x32_bf16 v[34:37], v[154:157], v[170:173], v[34:37]
	v_mfma_f32_16x16x32_bf16 v[34:37], v[158:161], v[174:177], v[34:37]
	v_mfma_f32_16x16x32_bf16 v[38:41], v[150:153], v[174:177], v[38:41]
	v_mfma_f32_16x16x32_bf16 v[38:41], v[146:149], v[170:173], v[38:41]
	v_mfma_f32_16x16x32_bf16 v[20:23], v[146:149], v[188:191], v[20:23]
	v_mfma_f32_16x16x32_bf16 v[20:23], v[150:153], v[192:195], v[20:23]
	v_mfma_f32_16x16x32_bf16 v[16:19], v[158:161], v[192:195], v[16:19]
	v_mfma_f32_16x16x32_bf16 v[16:19], v[154:157], v[188:191], v[16:19]
	v_mfma_f32_16x16x32_bf16 v[0:3], v[154:157], v[196:199], v[0:3]
	v_mfma_f32_16x16x32_bf16 v[0:3], v[158:161], v[200:203], v[0:3]
	v_mfma_f32_16x16x32_bf16 v[4:7], v[150:153], v[200:203], v[4:7]
	v_mfma_f32_16x16x32_bf16 v[4:7], v[146:149], v[196:199], v[4:7]
	s_setprio 0
	s_barrier
	s_add_i32 s54, 0, 0x18000
	s_add_i32 s55, 0, 0x1c000
	v_add_u32_e32 v142, s54, v212
	v_add_u32_e32 v158, s55, v212
	ds_read_b128 v[130:133], v142
	ds_read_b128 v[134:137], v142 offset:1024
	ds_read_b128 v[138:141], v142 offset:2048
	ds_read_b128 v[142:145], v142 offset:3072
	ds_read_b128 v[146:149], v158
	ds_read_b128 v[150:153], v158 offset:1024
	ds_read_b128 v[154:157], v158 offset:2048
	ds_read_b128 v[158:161], v158 offset:3072
	s_add_u32 s28, s28, 0x80000
	s_addc_u32 s29, s29, 0
	s_mov_b32 m0, s33
	ds_read_b128 v[162:165], v213 offset:32768
	ds_read_b128 v[166:169], v213 offset:33792
	ds_read_b128 v[170:173], v213 offset:34816
	ds_read_b128 v[174:177], v213 offset:35840
	ds_read_b128 v[188:191], v213 offset:36864
	ds_read_b128 v[192:195], v213 offset:37888
	ds_read_b128 v[196:199], v213 offset:38912
	ds_read_b128 v[200:203], v213 offset:39936
	global_load_lds_dwordx4 v178, s[28:29]
	s_mov_b32 m0, s36
	s_nop 0
	global_load_lds_dwordx4 v180, s[28:29]
	s_waitcnt vmcnt(8)
	s_waitcnt lgkmcnt(0)
	s_barrier
	s_setprio 1
	v_mfma_f32_16x16x32_bf16 v[126:129], v[130:133], v[162:165], v[126:129]
	v_mfma_f32_16x16x32_bf16 v[126:129], v[134:137], v[166:169], v[126:129]
	v_mfma_f32_16x16x32_bf16 v[122:125], v[142:145], v[166:169], v[122:125]
	v_mfma_f32_16x16x32_bf16 v[122:125], v[138:141], v[162:165], v[122:125]
	v_mfma_f32_16x16x32_bf16 v[106:109], v[138:141], v[170:173], v[106:109]
	v_mfma_f32_16x16x32_bf16 v[106:109], v[142:145], v[174:177], v[106:109]
	v_mfma_f32_16x16x32_bf16 v[110:113], v[134:137], v[174:177], v[110:113]
	v_mfma_f32_16x16x32_bf16 v[110:113], v[130:133], v[170:173], v[110:113]
	v_mfma_f32_16x16x32_bf16 v[94:97], v[130:133], v[188:191], v[94:97]
	v_mfma_f32_16x16x32_bf16 v[94:97], v[134:137], v[192:195], v[94:97]
	v_mfma_f32_16x16x32_bf16 v[90:93], v[142:145], v[192:195], v[90:93]
	v_mfma_f32_16x16x32_bf16 v[90:93], v[138:141], v[188:191], v[90:93]
	v_mfma_f32_16x16x32_bf16 v[74:77], v[138:141], v[196:199], v[74:77]
	v_mfma_f32_16x16x32_bf16 v[74:77], v[142:145], v[200:203], v[74:77]
	v_mfma_f32_16x16x32_bf16 v[78:81], v[134:137], v[200:203], v[78:81]
	v_mfma_f32_16x16x32_bf16 v[78:81], v[130:133], v[196:199], v[78:81]
	v_mfma_f32_16x16x32_bf16 v[118:121], v[146:149], v[162:165], v[118:121]
	v_mfma_f32_16x16x32_bf16 v[118:121], v[150:153], v[166:169], v[118:121]
	v_mfma_f32_16x16x32_bf16 v[114:117], v[158:161], v[166:169], v[114:117]
	v_mfma_f32_16x16x32_bf16 v[114:117], v[154:157], v[162:165], v[114:117]
	v_mfma_f32_16x16x32_bf16 v[98:101], v[154:157], v[170:173], v[98:101]
	v_mfma_f32_16x16x32_bf16 v[98:101], v[158:161], v[174:177], v[98:101]
	v_mfma_f32_16x16x32_bf16 v[102:105], v[150:153], v[174:177], v[102:105]
	v_mfma_f32_16x16x32_bf16 v[102:105], v[146:149], v[170:173], v[102:105]
	v_mfma_f32_16x16x32_bf16 v[86:89], v[146:149], v[188:191], v[86:89]
	v_mfma_f32_16x16x32_bf16 v[86:89], v[150:153], v[192:195], v[86:89]
	v_mfma_f32_16x16x32_bf16 v[82:85], v[158:161], v[192:195], v[82:85]
	v_mfma_f32_16x16x32_bf16 v[82:85], v[154:157], v[188:191], v[82:85]
	v_mfma_f32_16x16x32_bf16 v[66:69], v[154:157], v[196:199], v[66:69]
	v_mfma_f32_16x16x32_bf16 v[66:69], v[158:161], v[200:203], v[66:69]
	v_mfma_f32_16x16x32_bf16 v[70:73], v[150:153], v[200:203], v[70:73]
	v_mfma_f32_16x16x32_bf16 v[70:73], v[146:149], v[196:199], v[70:73]
	s_setprio 0
	s_barrier
	s_add_i32 s28, s54, s1
	v_lshl_add_u64 v[204:205], v[204:205], 0, s[34:35]
	s_mov_b32 m0, s28
	ds_read_b128 v[162:165], v213 offset:49152
	ds_read_b128 v[166:169], v213 offset:50176
	ds_read_b128 v[170:173], v213 offset:51200
	ds_read_b128 v[174:177], v213 offset:52224
	ds_read_b128 v[188:191], v213 offset:53248
	ds_read_b128 v[192:195], v213 offset:54272
	ds_read_b128 v[196:199], v213 offset:55296
	ds_read_b128 v[200:203], v213 offset:56320
	global_load_lds_dwordx4 v[204:205], off
	s_add_i32 m0, s28, 0x2000
	s_add_u32 s28, s42, 0x80080
	v_lshl_add_u64 v[204:205], v[206:207], 0, s[34:35]
	s_addc_u32 s29, s43, 0
	s_add_i32 s42, s55, s1
	global_load_lds_dwordx4 v[204:205], off
	s_mov_b32 m0, s42
	s_nop 0
	global_load_lds_dwordx4 v32, s[28:29]
	s_add_i32 m0, s42, 0x2000
	s_nop 0
	global_load_lds_dwordx4 v182, s[28:29]
	v_lshl_add_u64 v[204:205], v[208:209], 0, s[34:35]
	s_mov_b32 m0, s44
	s_nop 0
	global_load_lds_dwordx4 v[204:205], off
	v_lshl_add_u64 v[204:205], v[214:215], 0, s[34:35]
	s_mov_b32 m0, s45
	s_nop 0
	global_load_lds_dwordx4 v[204:205], off
	s_waitcnt vmcnt(8)
	s_waitcnt lgkmcnt(0)
	s_barrier
	s_setprio 1
	v_mfma_f32_16x16x32_bf16 v[62:65], v[130:133], v[162:165], v[62:65]
	v_mfma_f32_16x16x32_bf16 v[62:65], v[134:137], v[166:169], v[62:65]
	v_mfma_f32_16x16x32_bf16 v[58:61], v[142:145], v[166:169], v[58:61]
	v_mfma_f32_16x16x32_bf16 v[58:61], v[138:141], v[162:165], v[58:61]
	v_mfma_f32_16x16x32_bf16 v[42:45], v[138:141], v[170:173], v[42:45]
	v_mfma_f32_16x16x32_bf16 v[42:45], v[142:145], v[174:177], v[42:45]
	v_mfma_f32_16x16x32_bf16 v[46:49], v[134:137], v[174:177], v[46:49]
	v_mfma_f32_16x16x32_bf16 v[46:49], v[130:133], v[170:173], v[46:49]
	v_mfma_f32_16x16x32_bf16 v[28:31], v[130:133], v[188:191], v[28:31]
	v_mfma_f32_16x16x32_bf16 v[28:31], v[134:137], v[192:195], v[28:31]
	v_mfma_f32_16x16x32_bf16 v[24:27], v[142:145], v[192:195], v[24:27]
	v_mfma_f32_16x16x32_bf16 v[24:27], v[138:141], v[188:191], v[24:27]
	v_mfma_f32_16x16x32_bf16 v[8:11], v[138:141], v[196:199], v[8:11]
	v_mfma_f32_16x16x32_bf16 v[8:11], v[142:145], v[200:203], v[8:11]
	v_mfma_f32_16x16x32_bf16 v[12:15], v[134:137], v[200:203], v[12:15]
	v_mfma_f32_16x16x32_bf16 v[12:15], v[130:133], v[196:199], v[12:15]
	v_mfma_f32_16x16x32_bf16 v[54:57], v[146:149], v[162:165], v[54:57]
	v_mfma_f32_16x16x32_bf16 v[54:57], v[150:153], v[166:169], v[54:57]
	v_mfma_f32_16x16x32_bf16 v[50:53], v[158:161], v[166:169], v[50:53]
	v_mfma_f32_16x16x32_bf16 v[50:53], v[154:157], v[162:165], v[50:53]
	v_mfma_f32_16x16x32_bf16 v[34:37], v[154:157], v[170:173], v[34:37]
	v_mfma_f32_16x16x32_bf16 v[34:37], v[158:161], v[174:177], v[34:37]
	v_mfma_f32_16x16x32_bf16 v[38:41], v[150:153], v[174:177], v[38:41]
	v_mfma_f32_16x16x32_bf16 v[38:41], v[146:149], v[170:173], v[38:41]
	v_mfma_f32_16x16x32_bf16 v[20:23], v[146:149], v[188:191], v[20:23]
	v_mfma_f32_16x16x32_bf16 v[20:23], v[150:153], v[192:195], v[20:23]
	v_mfma_f32_16x16x32_bf16 v[16:19], v[158:161], v[192:195], v[16:19]
	v_mfma_f32_16x16x32_bf16 v[16:19], v[154:157], v[188:191], v[16:19]
	v_mfma_f32_16x16x32_bf16 v[0:3], v[154:157], v[196:199], v[0:3]
	v_mfma_f32_16x16x32_bf16 v[0:3], v[158:161], v[200:203], v[0:3]
	v_mfma_f32_16x16x32_bf16 v[4:7], v[150:153], v[200:203], v[4:7]
	v_mfma_f32_16x16x32_bf16 v[4:7], v[146:149], v[196:199], v[4:7]
	s_setprio 0
	s_barrier
	s_add_i32 s53, s53, 2
	s_add_u32 s40, s40, 0x100
	s_addc_u32 s41, s41, 0
	s_add_u32 s51, s51, 0x100
	s_addc_u32 s52, s52, 0
	s_cmp_gt_u32 s53, 29
	s_cbranch_scc0 .LBB0_120
	s_and_b64 vcc, exec, s[18:19]
	s_cbranch_vccz .LBB0_123
	s_barrier

.LBB0_685:
	s_add_u32 s28, s16, s40
	s_addc_u32 s29, s17, s41
	s_add_u32 s28, s28, 0x100
	s_addc_u32 s29, s29, 0
	s_add_u32 s42, s52, s40
	s_addc_u32 s43, s53, s41
	s_add_i32 s56, 0, 0x10000
	s_cmpk_eq_i32 s40, 0xf00
	s_cselect_b32 s29, s39, s29
	s_cselect_b32 s28, s38, s28
	s_cselect_b32 s43, s23, s43
	s_cselect_b32 s42, s54, s42
	s_add_i32 s58, 0, 0x14000
	v_add_u32_e32 v146, s56, v190
	v_add_u32_e32 v162, s58, v190
	ds_read_b128 v[134:137], v146
	ds_read_b128 v[138:141], v146 offset:1024
	ds_read_b128 v[142:145], v146 offset:2048
	ds_read_b128 v[146:149], v146 offset:3072
	ds_read_b128 v[150:153], v162
	ds_read_b128 v[154:157], v162 offset:1024
	ds_read_b128 v[158:161], v162 offset:2048
	ds_read_b128 v[162:165], v162 offset:3072
	v_lshl_add_u64 v[212:213], v[130:131], 0, s[40:41]
	s_add_i32 m0, s24, 0xc000
	ds_read_b128 v[166:169], v191
	ds_read_b128 v[180:183], v191 offset:1024
	ds_read_b128 v[184:187], v191 offset:2048
	ds_read_b128 v[192:195], v191 offset:3072
	ds_read_b128 v[196:199], v191 offset:4096
	ds_read_b128 v[200:203], v191 offset:5120
	ds_read_b128 v[204:207], v191 offset:6144
	ds_read_b128 v[208:211], v191 offset:7168
	global_load_lds_dwordx4 v[212:213], off
	v_lshl_add_u64 v[212:213], v[132:133], 0, s[40:41]
	s_add_i32 m0, s24, 0xe000
	s_nop 0
	global_load_lds_dwordx4 v[212:213], off
	s_waitcnt vmcnt(8)
	s_waitcnt lgkmcnt(0)
	s_barrier
	s_setprio 1
	v_mfma_f32_16x16x32_bf16 v[82:85], v[134:137], v[166:169], v[82:85]
	v_mfma_f32_16x16x32_bf16 v[82:85], v[138:141], v[180:183], v[82:85]
	v_mfma_f32_16x16x32_bf16 v[78:81], v[146:149], v[180:183], v[78:81]
	v_mfma_f32_16x16x32_bf16 v[78:81], v[142:145], v[166:169], v[78:81]
	v_mfma_f32_16x16x32_bf16 v[70:73], v[142:145], v[184:187], v[70:73]
	v_mfma_f32_16x16x32_bf16 v[70:73], v[146:149], v[192:195], v[70:73]
	v_mfma_f32_16x16x32_bf16 v[74:77], v[138:141], v[192:195], v[74:77]
	v_mfma_f32_16x16x32_bf16 v[74:77], v[134:137], v[184:187], v[74:77]
	v_mfma_f32_16x16x32_bf16 v[66:69], v[134:137], v[196:199], v[66:69]
	v_mfma_f32_16x16x32_bf16 v[66:69], v[138:141], v[200:203], v[66:69]
	v_mfma_f32_16x16x32_bf16 v[62:65], v[146:149], v[200:203], v[62:65]
	v_mfma_f32_16x16x32_bf16 v[62:65], v[142:145], v[196:199], v[62:65]
	v_mfma_f32_16x16x32_bf16 v[54:57], v[142:145], v[204:207], v[54:57]
	v_mfma_f32_16x16x32_bf16 v[54:57], v[146:149], v[208:211], v[54:57]
	v_mfma_f32_16x16x32_bf16 v[58:61], v[138:141], v[208:211], v[58:61]
	v_mfma_f32_16x16x32_bf16 v[58:61], v[134:137], v[204:207], v[58:61]
	v_mfma_f32_16x16x32_bf16 v[50:53], v[150:153], v[166:169], v[50:53]
	v_mfma_f32_16x16x32_bf16 v[50:53], v[154:157], v[180:183], v[50:53]
	v_mfma_f32_16x16x32_bf16 v[46:49], v[162:165], v[180:183], v[46:49]
	v_mfma_f32_16x16x32_bf16 v[46:49], v[158:161], v[166:169], v[46:49]
	v_mfma_f32_16x16x32_bf16 v[38:41], v[158:161], v[184:187], v[38:41]
	v_mfma_f32_16x16x32_bf16 v[38:41], v[162:165], v[192:195], v[38:41]
	v_mfma_f32_16x16x32_bf16 v[42:45], v[154:157], v[192:195], v[42:45]
	v_mfma_f32_16x16x32_bf16 v[42:45], v[150:153], v[184:187], v[42:45]
	v_mfma_f32_16x16x32_bf16 v[34:37], v[150:153], v[196:199], v[34:37]
	v_mfma_f32_16x16x32_bf16 v[34:37], v[154:157], v[200:203], v[34:37]
	v_mfma_f32_16x16x32_bf16 v[28:31], v[162:165], v[200:203], v[28:31]
	v_mfma_f32_16x16x32_bf16 v[28:31], v[158:161], v[196:199], v[28:31]
	v_mfma_f32_16x16x32_bf16 v[20:23], v[158:161], v[204:207], v[20:23]
	v_mfma_f32_16x16x32_bf16 v[20:23], v[162:165], v[208:211], v[20:23]
	v_mfma_f32_16x16x32_bf16 v[24:27], v[154:157], v[208:211], v[24:27]
	v_mfma_f32_16x16x32_bf16 v[24:27], v[150:153], v[204:207], v[24:27]
	s_setprio 0
	s_barrier
	s_add_i32 s56, s56, s13
	v_lshl_add_u64 v[212:213], s[42:43], 0, v[32:33]
	s_mov_b32 m0, s56
	ds_read_b128 v[166:169], v191 offset:16384
	ds_read_b128 v[180:183], v191 offset:17408
	ds_read_b128 v[184:187], v191 offset:18432
	ds_read_b128 v[192:195], v191 offset:19456
	ds_read_b128 v[196:199], v191 offset:20480
	ds_read_b128 v[200:203], v191 offset:21504
	ds_read_b128 v[204:207], v191 offset:22528
	ds_read_b128 v[208:211], v191 offset:23552
	global_load_lds_dwordx4 v[212:213], off
	s_add_i32 m0, s56, 0x2000
	s_add_u32 s56, s42, 0x80000
	v_lshl_add_u64 v[214:215], s[42:43], 0, v[174:175]
	s_addc_u32 s57, s43, 0
	s_add_i32 s58, s58, s13
	global_load_lds_dwordx4 v[214:215], off
	s_mov_b32 m0, s58
	v_lshl_add_u64 v[220:221], s[28:29], 0, v[172:173]
	global_load_lds_dwordx4 v32, s[56:57]
	s_add_i32 m0, s58, 0x2000
	s_nop 0
	global_load_lds_dwordx4 v174, s[56:57]
	v_lshl_add_u64 v[216:217], s[28:29], 0, v[170:171]
	s_mov_b32 m0, s24
	s_nop 0
	global_load_lds_dwordx4 v[216:217], off
	s_mov_b32 m0, s25
	s_nop 0
	global_load_lds_dwordx4 v[220:221], off
	s_waitcnt vmcnt(8)
	s_waitcnt lgkmcnt(0)
	s_barrier
	s_setprio 1
	v_mfma_f32_16x16x32_bf16 v[16:19], v[134:137], v[166:169], v[16:19]
	v_mfma_f32_16x16x32_bf16 v[16:19], v[138:141], v[180:183], v[16:19]
	v_mfma_f32_16x16x32_bf16 v[12:15], v[146:149], v[180:183], v[12:15]
	v_mfma_f32_16x16x32_bf16 v[12:15], v[142:145], v[166:169], v[12:15]
	v_mfma_f32_16x16x32_bf16 v[4:7], v[142:145], v[184:187], v[4:7]
	v_mfma_f32_16x16x32_bf16 v[4:7], v[146:149], v[192:195], v[4:7]
	v_mfma_f32_16x16x32_bf16 v[8:11], v[138:141], v[192:195], v[8:11]
	v_mfma_f32_16x16x32_bf16 v[8:11], v[134:137], v[184:187], v[8:11]
	v_mfma_f32_16x16x32_bf16 v[0:3], v[134:137], v[196:199], v[0:3]
	v_mfma_f32_16x16x32_bf16 v[0:3], v[138:141], v[200:203], v[0:3]
	v_mfma_f32_16x16x32_bf16 v[86:89], v[146:149], v[200:203], v[86:89]
	v_mfma_f32_16x16x32_bf16 v[86:89], v[142:145], v[196:199], v[86:89]
	v_mfma_f32_16x16x32_bf16 v[94:97], v[142:145], v[204:207], v[94:97]
	v_mfma_f32_16x16x32_bf16 v[94:97], v[146:149], v[208:211], v[94:97]
	v_mfma_f32_16x16x32_bf16 v[90:93], v[138:141], v[208:211], v[90:93]
	v_mfma_f32_16x16x32_bf16 v[90:93], v[134:137], v[204:207], v[90:93]
	v_mfma_f32_16x16x32_bf16 v[98:101], v[150:153], v[166:169], v[98:101]
	v_mfma_f32_16x16x32_bf16 v[98:101], v[154:157], v[180:183], v[98:101]
	v_mfma_f32_16x16x32_bf16 v[102:105], v[162:165], v[180:183], v[102:105]
	v_mfma_f32_16x16x32_bf16 v[102:105], v[158:161], v[166:169], v[102:105]
	v_mfma_f32_16x16x32_bf16 v[110:113], v[158:161], v[184:187], v[110:113]
	v_mfma_f32_16x16x32_bf16 v[110:113], v[162:165], v[192:195], v[110:113]
	v_mfma_f32_16x16x32_bf16 v[106:109], v[154:157], v[192:195], v[106:109]
	v_mfma_f32_16x16x32_bf16 v[106:109], v[150:153], v[184:187], v[106:109]
	v_mfma_f32_16x16x32_bf16 v[114:117], v[150:153], v[196:199], v[114:117]
	v_mfma_f32_16x16x32_bf16 v[114:117], v[154:157], v[200:203], v[114:117]
	v_mfma_f32_16x16x32_bf16 v[118:121], v[162:165], v[200:203], v[118:121]
	v_mfma_f32_16x16x32_bf16 v[118:121], v[158:161], v[196:199], v[118:121]
	v_mfma_f32_16x16x32_bf16 v[126:129], v[158:161], v[204:207], v[126:129]
	v_mfma_f32_16x16x32_bf16 v[126:129], v[162:165], v[208:211], v[126:129]
	v_mfma_f32_16x16x32_bf16 v[122:125], v[154:157], v[208:211], v[122:125]
	v_mfma_f32_16x16x32_bf16 v[122:125], v[150:153], v[204:207], v[122:125]
	s_setprio 0
	s_barrier
	s_add_i32 s56, 0, 0x18000
	s_add_i32 s57, 0, 0x1c000
	v_add_u32_e32 v146, s56, v190
	v_add_u32_e32 v162, s57, v190
	ds_read_b128 v[134:137], v146
	ds_read_b128 v[138:141], v146 offset:1024
	ds_read_b128 v[142:145], v146 offset:2048
	ds_read_b128 v[146:149], v146 offset:3072
	ds_read_b128 v[150:153], v162
	ds_read_b128 v[154:157], v162 offset:1024
	ds_read_b128 v[158:161], v162 offset:2048
	ds_read_b128 v[162:165], v162 offset:3072
	s_add_u32 s28, s28, 0x80000
	s_addc_u32 s29, s29, 0
	s_mov_b32 m0, s33
	ds_read_b128 v[166:169], v191 offset:32768
	ds_read_b128 v[180:183], v191 offset:33792
	ds_read_b128 v[184:187], v191 offset:34816
	ds_read_b128 v[192:195], v191 offset:35840
	ds_read_b128 v[196:199], v191 offset:36864
	ds_read_b128 v[200:203], v191 offset:37888
	ds_read_b128 v[204:207], v191 offset:38912
	ds_read_b128 v[208:211], v191 offset:39936
	global_load_lds_dwordx4 v170, s[28:29]
	s_mov_b32 m0, s36
	s_nop 0
	global_load_lds_dwordx4 v172, s[28:29]
	s_waitcnt vmcnt(8)
	s_waitcnt lgkmcnt(0)
	s_barrier
	s_setprio 1
	v_mfma_f32_16x16x32_bf16 v[82:85], v[134:137], v[166:169], v[82:85]
	v_mfma_f32_16x16x32_bf16 v[82:85], v[138:141], v[180:183], v[82:85]
	v_mfma_f32_16x16x32_bf16 v[78:81], v[146:149], v[180:183], v[78:81]
	v_mfma_f32_16x16x32_bf16 v[78:81], v[142:145], v[166:169], v[78:81]
	v_mfma_f32_16x16x32_bf16 v[70:73], v[142:145], v[184:187], v[70:73]
	v_mfma_f32_16x16x32_bf16 v[70:73], v[146:149], v[192:195], v[70:73]
	v_mfma_f32_16x16x32_bf16 v[74:77], v[138:141], v[192:195], v[74:77]
	v_mfma_f32_16x16x32_bf16 v[74:77], v[134:137], v[184:187], v[74:77]
	v_mfma_f32_16x16x32_bf16 v[66:69], v[134:137], v[196:199], v[66:69]
	v_mfma_f32_16x16x32_bf16 v[66:69], v[138:141], v[200:203], v[66:69]
	v_mfma_f32_16x16x32_bf16 v[62:65], v[146:149], v[200:203], v[62:65]
	v_mfma_f32_16x16x32_bf16 v[62:65], v[142:145], v[196:199], v[62:65]
	v_mfma_f32_16x16x32_bf16 v[54:57], v[142:145], v[204:207], v[54:57]
	v_mfma_f32_16x16x32_bf16 v[54:57], v[146:149], v[208:211], v[54:57]
	v_mfma_f32_16x16x32_bf16 v[58:61], v[138:141], v[208:211], v[58:61]
	v_mfma_f32_16x16x32_bf16 v[58:61], v[134:137], v[204:207], v[58:61]
	v_mfma_f32_16x16x32_bf16 v[50:53], v[150:153], v[166:169], v[50:53]
	v_mfma_f32_16x16x32_bf16 v[50:53], v[154:157], v[180:183], v[50:53]
	v_mfma_f32_16x16x32_bf16 v[46:49], v[162:165], v[180:183], v[46:49]
	v_mfma_f32_16x16x32_bf16 v[46:49], v[158:161], v[166:169], v[46:49]
	v_mfma_f32_16x16x32_bf16 v[38:41], v[158:161], v[184:187], v[38:41]
	v_mfma_f32_16x16x32_bf16 v[38:41], v[162:165], v[192:195], v[38:41]
	v_mfma_f32_16x16x32_bf16 v[42:45], v[154:157], v[192:195], v[42:45]
	v_mfma_f32_16x16x32_bf16 v[42:45], v[150:153], v[184:187], v[42:45]
	v_mfma_f32_16x16x32_bf16 v[34:37], v[150:153], v[196:199], v[34:37]
	v_mfma_f32_16x16x32_bf16 v[34:37], v[154:157], v[200:203], v[34:37]
	v_mfma_f32_16x16x32_bf16 v[28:31], v[162:165], v[200:203], v[28:31]
	v_mfma_f32_16x16x32_bf16 v[28:31], v[158:161], v[196:199], v[28:31]
	v_mfma_f32_16x16x32_bf16 v[20:23], v[158:161], v[204:207], v[20:23]
	v_mfma_f32_16x16x32_bf16 v[20:23], v[162:165], v[208:211], v[20:23]
	v_mfma_f32_16x16x32_bf16 v[24:27], v[154:157], v[208:211], v[24:27]
	v_mfma_f32_16x16x32_bf16 v[24:27], v[150:153], v[204:207], v[24:27]
	s_setprio 0
	s_barrier
	s_add_i32 s28, s56, s13
	v_lshl_add_u64 v[212:213], v[212:213], 0, s[34:35]
	s_mov_b32 m0, s28
	ds_read_b128 v[166:169], v191 offset:49152
	ds_read_b128 v[180:183], v191 offset:50176
	ds_read_b128 v[184:187], v191 offset:51200
	ds_read_b128 v[192:195], v191 offset:52224
	ds_read_b128 v[196:199], v191 offset:53248
	ds_read_b128 v[200:203], v191 offset:54272
	ds_read_b128 v[204:207], v191 offset:55296
	ds_read_b128 v[208:211], v191 offset:56320
	global_load_lds_dwordx4 v[212:213], off
	s_add_i32 m0, s28, 0x2000
	s_add_u32 s28, s42, 0x80080
	v_lshl_add_u64 v[212:213], v[214:215], 0, s[34:35]
	s_addc_u32 s29, s43, 0
	s_add_i32 s42, s57, s13
	global_load_lds_dwordx4 v[212:213], off
	s_mov_b32 m0, s42
	s_nop 0
	global_load_lds_dwordx4 v32, s[28:29]
	s_add_i32 m0, s42, 0x2000
	s_nop 0
	global_load_lds_dwordx4 v174, s[28:29]
	v_lshl_add_u64 v[212:213], v[216:217], 0, s[34:35]
	s_mov_b32 m0, s45
	s_nop 0
	global_load_lds_dwordx4 v[212:213], off
	v_lshl_add_u64 v[212:213], v[220:221], 0, s[34:35]
	s_mov_b32 m0, s46
	s_nop 0
	global_load_lds_dwordx4 v[212:213], off
	s_waitcnt vmcnt(8)
	s_waitcnt lgkmcnt(0)
	s_barrier
	s_setprio 1
	v_mfma_f32_16x16x32_bf16 v[16:19], v[134:137], v[166:169], v[16:19]
	v_mfma_f32_16x16x32_bf16 v[16:19], v[138:141], v[180:183], v[16:19]
	v_mfma_f32_16x16x32_bf16 v[12:15], v[146:149], v[180:183], v[12:15]
	v_mfma_f32_16x16x32_bf16 v[12:15], v[142:145], v[166:169], v[12:15]
	v_mfma_f32_16x16x32_bf16 v[4:7], v[142:145], v[184:187], v[4:7]
	v_mfma_f32_16x16x32_bf16 v[4:7], v[146:149], v[192:195], v[4:7]
	v_mfma_f32_16x16x32_bf16 v[8:11], v[138:141], v[192:195], v[8:11]
	v_mfma_f32_16x16x32_bf16 v[8:11], v[134:137], v[184:187], v[8:11]
	v_mfma_f32_16x16x32_bf16 v[0:3], v[134:137], v[196:199], v[0:3]
	v_mfma_f32_16x16x32_bf16 v[0:3], v[138:141], v[200:203], v[0:3]
	v_mfma_f32_16x16x32_bf16 v[86:89], v[146:149], v[200:203], v[86:89]
	v_mfma_f32_16x16x32_bf16 v[86:89], v[142:145], v[196:199], v[86:89]
	v_mfma_f32_16x16x32_bf16 v[94:97], v[142:145], v[204:207], v[94:97]
	v_mfma_f32_16x16x32_bf16 v[94:97], v[146:149], v[208:211], v[94:97]
	v_mfma_f32_16x16x32_bf16 v[90:93], v[138:141], v[208:211], v[90:93]
	v_mfma_f32_16x16x32_bf16 v[90:93], v[134:137], v[204:207], v[90:93]
	v_mfma_f32_16x16x32_bf16 v[98:101], v[150:153], v[166:169], v[98:101]
	v_mfma_f32_16x16x32_bf16 v[98:101], v[154:157], v[180:183], v[98:101]
	v_mfma_f32_16x16x32_bf16 v[102:105], v[162:165], v[180:183], v[102:105]
	v_mfma_f32_16x16x32_bf16 v[102:105], v[158:161], v[166:169], v[102:105]
	v_mfma_f32_16x16x32_bf16 v[110:113], v[158:161], v[184:187], v[110:113]
	v_mfma_f32_16x16x32_bf16 v[110:113], v[162:165], v[192:195], v[110:113]
	v_mfma_f32_16x16x32_bf16 v[106:109], v[154:157], v[192:195], v[106:109]
	v_mfma_f32_16x16x32_bf16 v[106:109], v[150:153], v[184:187], v[106:109]
	v_mfma_f32_16x16x32_bf16 v[114:117], v[150:153], v[196:199], v[114:117]
	v_mfma_f32_16x16x32_bf16 v[114:117], v[154:157], v[200:203], v[114:117]
	v_mfma_f32_16x16x32_bf16 v[118:121], v[162:165], v[200:203], v[118:121]
	v_mfma_f32_16x16x32_bf16 v[118:121], v[158:161], v[196:199], v[118:121]
	v_mfma_f32_16x16x32_bf16 v[126:129], v[158:161], v[204:207], v[126:129]
	v_mfma_f32_16x16x32_bf16 v[126:129], v[162:165], v[208:211], v[126:129]
	v_mfma_f32_16x16x32_bf16 v[122:125], v[154:157], v[208:211], v[122:125]
	v_mfma_f32_16x16x32_bf16 v[122:125], v[150:153], v[204:207], v[122:125]
	s_setprio 0
	s_barrier
	s_add_i32 s55, s55, 2
	s_add_u32 s40, s40, 0x100
	s_addc_u32 s41, s41, 0
	s_cmp_gt_u32 s55, 29
	s_cbranch_scc0 .LBB0_685
	s_and_b64 vcc, exec, s[18:19]
	s_cbranch_vccz .LBB0_688
	s_barrier

.LBB0_755:
	s_add_u32 s6, s4, 0x100
	s_addc_u32 s7, s5, 0
	s_add_i32 s52, 0, 0x10000
	s_cmpk_eq_i32 s51, 0x54
	s_cselect_b32 s29, s23, s7
	s_cselect_b32 s28, s22, s6
	s_cselect_b32 s31, s27, s50
	s_cselect_b32 s30, s26, s33
	s_add_i32 s53, 0, 0x14000
	v_add_u32_e32 v142, s52, v242
	v_add_u32_e32 v158, s53, v242
	ds_read_b128 v[130:133], v142
	ds_read_b128 v[134:137], v142 offset:1024
	ds_read_b128 v[138:141], v142 offset:2048
	ds_read_b128 v[142:145], v142 offset:3072
	ds_read_b128 v[146:149], v158
	ds_read_b128 v[150:153], v158 offset:1024
	ds_read_b128 v[154:157], v158 offset:2048
	ds_read_b128 v[158:161], v158 offset:3072
	s_add_i32 m0, s36, 0xc000
	ds_read_b128 v[162:165], v243
	ds_read_b128 v[166:169], v243 offset:1024
	ds_read_b128 v[170:173], v243 offset:2048
	ds_read_b128 v[174:177], v243 offset:3072
	ds_read_b128 v[178:181], v243 offset:4096
	ds_read_b128 v[182:185], v243 offset:5120
	ds_read_b128 v[186:189], v243 offset:6144
	ds_read_b128 v[190:193], v243 offset:7168
	global_load_lds_dwordx4 v202, s[4:5]
	s_add_i32 m0, s36, 0xe000
	s_nop 0
	global_load_lds_dwordx4 v204, s[4:5]
	s_waitcnt vmcnt(8)
	s_waitcnt lgkmcnt(0)
	s_barrier
	s_setprio 1
	v_mfma_f32_16x16x32_bf16 v[126:129], v[130:133], v[162:165], v[126:129]
	v_mfma_f32_16x16x32_bf16 v[126:129], v[134:137], v[166:169], v[126:129]
	v_mfma_f32_16x16x32_bf16 v[122:125], v[142:145], v[166:169], v[122:125]
	v_mfma_f32_16x16x32_bf16 v[122:125], v[138:141], v[162:165], v[122:125]
	v_mfma_f32_16x16x32_bf16 v[106:109], v[138:141], v[170:173], v[106:109]
	v_mfma_f32_16x16x32_bf16 v[106:109], v[142:145], v[174:177], v[106:109]
	v_mfma_f32_16x16x32_bf16 v[110:113], v[134:137], v[174:177], v[110:113]
	v_mfma_f32_16x16x32_bf16 v[110:113], v[130:133], v[170:173], v[110:113]
	v_mfma_f32_16x16x32_bf16 v[94:97], v[130:133], v[178:181], v[94:97]
	v_mfma_f32_16x16x32_bf16 v[94:97], v[134:137], v[182:185], v[94:97]
	v_mfma_f32_16x16x32_bf16 v[90:93], v[142:145], v[182:185], v[90:93]
	v_mfma_f32_16x16x32_bf16 v[90:93], v[138:141], v[178:181], v[90:93]
	v_mfma_f32_16x16x32_bf16 v[74:77], v[138:141], v[186:189], v[74:77]
	v_mfma_f32_16x16x32_bf16 v[74:77], v[142:145], v[190:193], v[74:77]
	v_mfma_f32_16x16x32_bf16 v[78:81], v[134:137], v[190:193], v[78:81]
	v_mfma_f32_16x16x32_bf16 v[78:81], v[130:133], v[186:189], v[78:81]
	v_mfma_f32_16x16x32_bf16 v[118:121], v[146:149], v[162:165], v[118:121]
	v_mfma_f32_16x16x32_bf16 v[118:121], v[150:153], v[166:169], v[118:121]
	v_mfma_f32_16x16x32_bf16 v[114:117], v[158:161], v[166:169], v[114:117]
	v_mfma_f32_16x16x32_bf16 v[114:117], v[154:157], v[162:165], v[114:117]
	v_mfma_f32_16x16x32_bf16 v[98:101], v[154:157], v[170:173], v[98:101]
	v_mfma_f32_16x16x32_bf16 v[98:101], v[158:161], v[174:177], v[98:101]
	v_mfma_f32_16x16x32_bf16 v[102:105], v[150:153], v[174:177], v[102:105]
	v_mfma_f32_16x16x32_bf16 v[102:105], v[146:149], v[170:173], v[102:105]
	v_mfma_f32_16x16x32_bf16 v[86:89], v[146:149], v[178:181], v[86:89]
	v_mfma_f32_16x16x32_bf16 v[86:89], v[150:153], v[182:185], v[86:89]
	v_mfma_f32_16x16x32_bf16 v[82:85], v[158:161], v[182:185], v[82:85]
	v_mfma_f32_16x16x32_bf16 v[82:85], v[154:157], v[178:181], v[82:85]
	v_mfma_f32_16x16x32_bf16 v[66:69], v[154:157], v[186:189], v[66:69]
	v_mfma_f32_16x16x32_bf16 v[66:69], v[158:161], v[190:193], v[66:69]
	v_mfma_f32_16x16x32_bf16 v[70:73], v[150:153], v[190:193], v[70:73]
	v_mfma_f32_16x16x32_bf16 v[70:73], v[146:149], v[186:189], v[70:73]
	s_setprio 0
	s_barrier
	s_add_i32 s4, s52, s1
	v_lshl_add_u64 v[194:195], s[30:31], 0, v[32:33]
	s_mov_b32 m0, s4
	ds_read_b128 v[162:165], v243 offset:16384
	ds_read_b128 v[166:169], v243 offset:17408
	ds_read_b128 v[170:173], v243 offset:18432
	ds_read_b128 v[174:177], v243 offset:19456
	ds_read_b128 v[178:181], v243 offset:20480
	ds_read_b128 v[182:185], v243 offset:21504
	ds_read_b128 v[186:189], v243 offset:22528
	ds_read_b128 v[190:193], v243 offset:23552
	global_load_lds_dwordx4 v[194:195], off
	s_add_i32 m0, s4, 0x2000
	s_add_u32 s4, s30, 0x160000
	v_lshl_add_u64 v[206:207], s[30:31], 0, v[200:201]
	s_addc_u32 s5, s31, 0
	s_add_i32 s52, s53, s1
	global_load_lds_dwordx4 v[206:207], off
	s_mov_b32 m0, s52
	v_lshl_add_u64 v[210:211], s[28:29], 0, v[198:199]
	global_load_lds_dwordx4 v32, s[4:5]
	s_add_i32 m0, s52, 0x2000
	s_nop 0
	global_load_lds_dwordx4 v200, s[4:5]
	v_lshl_add_u64 v[208:209], s[28:29], 0, v[196:197]
	s_mov_b32 m0, s36
	s_nop 0
	global_load_lds_dwordx4 v[208:209], off
	s_mov_b32 m0, s38
	s_nop 0
	global_load_lds_dwordx4 v[210:211], off
	s_waitcnt vmcnt(8)
	s_waitcnt lgkmcnt(0)
	s_barrier
	s_setprio 1
	v_mfma_f32_16x16x32_bf16 v[62:65], v[130:133], v[162:165], v[62:65]
	v_mfma_f32_16x16x32_bf16 v[62:65], v[134:137], v[166:169], v[62:65]
	v_mfma_f32_16x16x32_bf16 v[58:61], v[142:145], v[166:169], v[58:61]
	v_mfma_f32_16x16x32_bf16 v[58:61], v[138:141], v[162:165], v[58:61]
	v_mfma_f32_16x16x32_bf16 v[42:45], v[138:141], v[170:173], v[42:45]
	v_mfma_f32_16x16x32_bf16 v[42:45], v[142:145], v[174:177], v[42:45]
	v_mfma_f32_16x16x32_bf16 v[46:49], v[134:137], v[174:177], v[46:49]
	v_mfma_f32_16x16x32_bf16 v[46:49], v[130:133], v[170:173], v[46:49]
	v_mfma_f32_16x16x32_bf16 v[28:31], v[130:133], v[178:181], v[28:31]
	v_mfma_f32_16x16x32_bf16 v[28:31], v[134:137], v[182:185], v[28:31]
	v_mfma_f32_16x16x32_bf16 v[24:27], v[142:145], v[182:185], v[24:27]
	v_mfma_f32_16x16x32_bf16 v[24:27], v[138:141], v[178:181], v[24:27]
	v_mfma_f32_16x16x32_bf16 v[8:11], v[138:141], v[186:189], v[8:11]
	v_mfma_f32_16x16x32_bf16 v[8:11], v[142:145], v[190:193], v[8:11]
	v_mfma_f32_16x16x32_bf16 v[12:15], v[134:137], v[190:193], v[12:15]
	v_mfma_f32_16x16x32_bf16 v[12:15], v[130:133], v[186:189], v[12:15]
	v_mfma_f32_16x16x32_bf16 v[54:57], v[146:149], v[162:165], v[54:57]
	v_mfma_f32_16x16x32_bf16 v[54:57], v[150:153], v[166:169], v[54:57]
	v_mfma_f32_16x16x32_bf16 v[50:53], v[158:161], v[166:169], v[50:53]
	v_mfma_f32_16x16x32_bf16 v[50:53], v[154:157], v[162:165], v[50:53]
	v_mfma_f32_16x16x32_bf16 v[34:37], v[154:157], v[170:173], v[34:37]
	v_mfma_f32_16x16x32_bf16 v[34:37], v[158:161], v[174:177], v[34:37]
	v_mfma_f32_16x16x32_bf16 v[38:41], v[150:153], v[174:177], v[38:41]
	v_mfma_f32_16x16x32_bf16 v[38:41], v[146:149], v[170:173], v[38:41]
	v_mfma_f32_16x16x32_bf16 v[20:23], v[146:149], v[178:181], v[20:23]
	v_mfma_f32_16x16x32_bf16 v[20:23], v[150:153], v[182:185], v[20:23]
	v_mfma_f32_16x16x32_bf16 v[16:19], v[158:161], v[182:185], v[16:19]
	v_mfma_f32_16x16x32_bf16 v[16:19], v[154:157], v[178:181], v[16:19]
	v_mfma_f32_16x16x32_bf16 v[0:3], v[154:157], v[186:189], v[0:3]
	v_mfma_f32_16x16x32_bf16 v[0:3], v[158:161], v[190:193], v[0:3]
	v_mfma_f32_16x16x32_bf16 v[4:7], v[150:153], v[190:193], v[4:7]
	v_mfma_f32_16x16x32_bf16 v[4:7], v[146:149], v[186:189], v[4:7]
	s_setprio 0
	s_barrier
	s_add_i32 s52, 0, 0x18000
	s_add_i32 s53, 0, 0x1c000
	v_add_u32_e32 v142, s52, v242
	v_add_u32_e32 v158, s53, v242
	ds_read_b128 v[130:133], v142
	ds_read_b128 v[134:137], v142 offset:1024
	ds_read_b128 v[138:141], v142 offset:2048
	ds_read_b128 v[142:145], v142 offset:3072
	ds_read_b128 v[146:149], v158
	ds_read_b128 v[150:153], v158 offset:1024
	ds_read_b128 v[154:157], v158 offset:2048
	ds_read_b128 v[158:161], v158 offset:3072
	s_add_u32 s4, s28, 0x160000
	s_addc_u32 s5, s29, 0
	s_mov_b32 m0, s39
	ds_read_b128 v[162:165], v243 offset:32768
	ds_read_b128 v[166:169], v243 offset:33792
	ds_read_b128 v[170:173], v243 offset:34816
	ds_read_b128 v[174:177], v243 offset:35840
	ds_read_b128 v[178:181], v243 offset:36864
	ds_read_b128 v[182:185], v243 offset:37888
	ds_read_b128 v[186:189], v243 offset:38912
	ds_read_b128 v[190:193], v243 offset:39936
	global_load_lds_dwordx4 v196, s[4:5]
	s_mov_b32 m0, s42
	s_nop 0
	global_load_lds_dwordx4 v198, s[4:5]
	s_waitcnt vmcnt(8)
	s_waitcnt lgkmcnt(0)
	s_barrier
	s_setprio 1
	v_mfma_f32_16x16x32_bf16 v[126:129], v[130:133], v[162:165], v[126:129]
	v_mfma_f32_16x16x32_bf16 v[126:129], v[134:137], v[166:169], v[126:129]
	v_mfma_f32_16x16x32_bf16 v[122:125], v[142:145], v[166:169], v[122:125]
	v_mfma_f32_16x16x32_bf16 v[122:125], v[138:141], v[162:165], v[122:125]
	v_mfma_f32_16x16x32_bf16 v[106:109], v[138:141], v[170:173], v[106:109]
	v_mfma_f32_16x16x32_bf16 v[106:109], v[142:145], v[174:177], v[106:109]
	v_mfma_f32_16x16x32_bf16 v[110:113], v[134:137], v[174:177], v[110:113]
	v_mfma_f32_16x16x32_bf16 v[110:113], v[130:133], v[170:173], v[110:113]
	v_mfma_f32_16x16x32_bf16 v[94:97], v[130:133], v[178:181], v[94:97]
	v_mfma_f32_16x16x32_bf16 v[94:97], v[134:137], v[182:185], v[94:97]
	v_mfma_f32_16x16x32_bf16 v[90:93], v[142:145], v[182:185], v[90:93]
	v_mfma_f32_16x16x32_bf16 v[90:93], v[138:141], v[178:181], v[90:93]
	v_mfma_f32_16x16x32_bf16 v[74:77], v[138:141], v[186:189], v[74:77]
	v_mfma_f32_16x16x32_bf16 v[74:77], v[142:145], v[190:193], v[74:77]
	v_mfma_f32_16x16x32_bf16 v[78:81], v[134:137], v[190:193], v[78:81]
	v_mfma_f32_16x16x32_bf16 v[78:81], v[130:133], v[186:189], v[78:81]
	v_mfma_f32_16x16x32_bf16 v[118:121], v[146:149], v[162:165], v[118:121]
	v_mfma_f32_16x16x32_bf16 v[118:121], v[150:153], v[166:169], v[118:121]
	v_mfma_f32_16x16x32_bf16 v[114:117], v[158:161], v[166:169], v[114:117]
	v_mfma_f32_16x16x32_bf16 v[114:117], v[154:157], v[162:165], v[114:117]
	v_mfma_f32_16x16x32_bf16 v[98:101], v[154:157], v[170:173], v[98:101]
	v_mfma_f32_16x16x32_bf16 v[98:101], v[158:161], v[174:177], v[98:101]
	v_mfma_f32_16x16x32_bf16 v[102:105], v[150:153], v[174:177], v[102:105]
	v_mfma_f32_16x16x32_bf16 v[102:105], v[146:149], v[170:173], v[102:105]
	v_mfma_f32_16x16x32_bf16 v[86:89], v[146:149], v[178:181], v[86:89]
	v_mfma_f32_16x16x32_bf16 v[86:89], v[150:153], v[182:185], v[86:89]
	v_mfma_f32_16x16x32_bf16 v[82:85], v[158:161], v[182:185], v[82:85]
	v_mfma_f32_16x16x32_bf16 v[82:85], v[154:157], v[178:181], v[82:85]
	v_mfma_f32_16x16x32_bf16 v[66:69], v[154:157], v[186:189], v[66:69]
	v_mfma_f32_16x16x32_bf16 v[66:69], v[158:161], v[190:193], v[66:69]
	v_mfma_f32_16x16x32_bf16 v[70:73], v[150:153], v[190:193], v[70:73]
	v_mfma_f32_16x16x32_bf16 v[70:73], v[146:149], v[186:189], v[70:73]
	s_setprio 0
	s_barrier
	s_add_i32 s4, s52, s1
	v_lshl_add_u64 v[194:195], v[194:195], 0, s[34:35]
	s_mov_b32 m0, s4
	ds_read_b128 v[162:165], v243 offset:49152
	ds_read_b128 v[166:169], v243 offset:50176
	ds_read_b128 v[170:173], v243 offset:51200
	ds_read_b128 v[174:177], v243 offset:52224
	ds_read_b128 v[178:181], v243 offset:53248
	ds_read_b128 v[182:185], v243 offset:54272
	ds_read_b128 v[186:189], v243 offset:55296
	ds_read_b128 v[190:193], v243 offset:56320
	global_load_lds_dwordx4 v[194:195], off
	s_add_i32 m0, s4, 0x2000
	s_add_u32 s4, s30, 0x160080
	v_lshl_add_u64 v[194:195], v[206:207], 0, s[34:35]
	s_addc_u32 s5, s31, 0
	s_add_i32 s28, s53, s1
	global_load_lds_dwordx4 v[194:195], off
	s_mov_b32 m0, s28
	s_nop 0
	global_load_lds_dwordx4 v32, s[4:5]
	s_add_i32 m0, s28, 0x2000
	s_nop 0
	global_load_lds_dwordx4 v200, s[4:5]
	v_lshl_add_u64 v[194:195], v[208:209], 0, s[34:35]
	s_mov_b32 m0, s44
	s_nop 0
	global_load_lds_dwordx4 v[194:195], off
	v_lshl_add_u64 v[194:195], v[210:211], 0, s[34:35]
	s_mov_b32 m0, s45
	s_nop 0
	global_load_lds_dwordx4 v[194:195], off
	s_waitcnt vmcnt(8)
	s_waitcnt lgkmcnt(0)
	s_barrier
	s_setprio 1
	v_mfma_f32_16x16x32_bf16 v[62:65], v[130:133], v[162:165], v[62:65]
	v_mfma_f32_16x16x32_bf16 v[62:65], v[134:137], v[166:169], v[62:65]
	v_mfma_f32_16x16x32_bf16 v[58:61], v[142:145], v[166:169], v[58:61]
	v_mfma_f32_16x16x32_bf16 v[58:61], v[138:141], v[162:165], v[58:61]
	v_mfma_f32_16x16x32_bf16 v[42:45], v[138:141], v[170:173], v[42:45]
	v_mfma_f32_16x16x32_bf16 v[42:45], v[142:145], v[174:177], v[42:45]
	v_mfma_f32_16x16x32_bf16 v[46:49], v[134:137], v[174:177], v[46:49]
	v_mfma_f32_16x16x32_bf16 v[46:49], v[130:133], v[170:173], v[46:49]
	v_mfma_f32_16x16x32_bf16 v[28:31], v[130:133], v[178:181], v[28:31]
	v_mfma_f32_16x16x32_bf16 v[28:31], v[134:137], v[182:185], v[28:31]
	v_mfma_f32_16x16x32_bf16 v[24:27], v[142:145], v[182:185], v[24:27]
	v_mfma_f32_16x16x32_bf16 v[24:27], v[138:141], v[178:181], v[24:27]
	v_mfma_f32_16x16x32_bf16 v[8:11], v[138:141], v[186:189], v[8:11]
	v_mfma_f32_16x16x32_bf16 v[8:11], v[142:145], v[190:193], v[8:11]
	v_mfma_f32_16x16x32_bf16 v[12:15], v[134:137], v[190:193], v[12:15]
	v_mfma_f32_16x16x32_bf16 v[12:15], v[130:133], v[186:189], v[12:15]
	v_mfma_f32_16x16x32_bf16 v[54:57], v[146:149], v[162:165], v[54:57]
	v_mfma_f32_16x16x32_bf16 v[54:57], v[150:153], v[166:169], v[54:57]
	v_mfma_f32_16x16x32_bf16 v[50:53], v[158:161], v[166:169], v[50:53]
	v_mfma_f32_16x16x32_bf16 v[50:53], v[154:157], v[162:165], v[50:53]
	v_mfma_f32_16x16x32_bf16 v[34:37], v[154:157], v[170:173], v[34:37]
	v_mfma_f32_16x16x32_bf16 v[34:37], v[158:161], v[174:177], v[34:37]
	v_mfma_f32_16x16x32_bf16 v[38:41], v[150:153], v[174:177], v[38:41]
	v_mfma_f32_16x16x32_bf16 v[38:41], v[146:149], v[170:173], v[38:41]
	v_mfma_f32_16x16x32_bf16 v[20:23], v[146:149], v[178:181], v[20:23]
	v_mfma_f32_16x16x32_bf16 v[20:23], v[150:153], v[182:185], v[20:23]
	v_mfma_f32_16x16x32_bf16 v[16:19], v[158:161], v[182:185], v[16:19]
	v_mfma_f32_16x16x32_bf16 v[16:19], v[154:157], v[178:181], v[16:19]
	v_mfma_f32_16x16x32_bf16 v[0:3], v[154:157], v[186:189], v[0:3]
	v_mfma_f32_16x16x32_bf16 v[0:3], v[158:161], v[190:193], v[0:3]
	v_mfma_f32_16x16x32_bf16 v[4:7], v[150:153], v[190:193], v[4:7]
	v_mfma_f32_16x16x32_bf16 v[4:7], v[146:149], v[186:189], v[4:7]
	s_setprio 0
	s_barrier
	s_add_i32 s51, s51, 2
	s_add_u32 s33, s33, 0x100
	s_addc_u32 s50, s50, 0
	s_cmpk_gt_u32 s51, 0x55
	s_mov_b64 s[4:5], s[6:7]
	s_cbranch_scc0 .LBB0_755
	s_and_b64 vcc, exec, s[18:19]
	s_cbranch_vccz .LBB0_758
	s_barrier

.LBB0_888:
	s_add_u32 s38, s16, s30
	s_addc_u32 s39, s17, s31
	s_add_u32 s38, s38, 0x100
	s_addc_u32 s39, s39, 0
	s_add_u32 s54, s50, s30
	s_addc_u32 s55, s51, s31
	s_add_i32 s56, 0, 0x10000
	s_cmpk_eq_i32 s30, 0xf00
	s_cselect_b32 s41, s29, s39
	s_cselect_b32 s40, s28, s38
	s_cselect_b32 s39, s21, s55
	s_cselect_b32 s38, s52, s54
	s_add_i32 s57, 0, 0x14000
	v_add_u32_e32 v146, s56, v178
	v_add_u32_e32 v172, s57, v178
	ds_read_b128 v[134:137], v146
	ds_read_b128 v[138:141], v146 offset:1024
	ds_read_b128 v[142:145], v146 offset:2048
	ds_read_b128 v[146:149], v146 offset:3072
	ds_read_b128 v[150:153], v172
	ds_read_b128 v[154:157], v172 offset:1024
	ds_read_b128 v[158:161], v172 offset:2048
	ds_read_b128 v[172:175], v172 offset:3072
	v_lshl_add_u64 v[212:213], v[130:131], 0, s[30:31]
	s_add_i32 m0, s24, 0xc000
	ds_read_b128 v[180:183], v179
	ds_read_b128 v[184:187], v179 offset:1024
	ds_read_b128 v[188:191], v179 offset:2048
	ds_read_b128 v[192:195], v179 offset:3072
	ds_read_b128 v[196:199], v179 offset:4096
	ds_read_b128 v[200:203], v179 offset:5120
	ds_read_b128 v[204:207], v179 offset:6144
	ds_read_b128 v[208:211], v179 offset:7168
	global_load_lds_dwordx4 v[212:213], off
	v_lshl_add_u64 v[212:213], v[132:133], 0, s[30:31]
	s_add_i32 m0, s24, 0xe000
	s_nop 0
	global_load_lds_dwordx4 v[212:213], off
	s_waitcnt vmcnt(8)
	s_waitcnt lgkmcnt(0)
	s_barrier
	s_setprio 1
	v_mfma_f32_16x16x32_bf16 v[82:85], v[134:137], v[180:183], v[82:85]
	v_mfma_f32_16x16x32_bf16 v[82:85], v[138:141], v[184:187], v[82:85]
	v_mfma_f32_16x16x32_bf16 v[78:81], v[146:149], v[184:187], v[78:81]
	v_mfma_f32_16x16x32_bf16 v[78:81], v[142:145], v[180:183], v[78:81]
	v_mfma_f32_16x16x32_bf16 v[70:73], v[142:145], v[188:191], v[70:73]
	v_mfma_f32_16x16x32_bf16 v[70:73], v[146:149], v[192:195], v[70:73]
	v_mfma_f32_16x16x32_bf16 v[74:77], v[138:141], v[192:195], v[74:77]
	v_mfma_f32_16x16x32_bf16 v[74:77], v[134:137], v[188:191], v[74:77]
	v_mfma_f32_16x16x32_bf16 v[66:69], v[134:137], v[196:199], v[66:69]
	v_mfma_f32_16x16x32_bf16 v[66:69], v[138:141], v[200:203], v[66:69]
	v_mfma_f32_16x16x32_bf16 v[62:65], v[146:149], v[200:203], v[62:65]
	v_mfma_f32_16x16x32_bf16 v[62:65], v[142:145], v[196:199], v[62:65]
	v_mfma_f32_16x16x32_bf16 v[54:57], v[142:145], v[204:207], v[54:57]
	v_mfma_f32_16x16x32_bf16 v[54:57], v[146:149], v[208:211], v[54:57]
	v_mfma_f32_16x16x32_bf16 v[58:61], v[138:141], v[208:211], v[58:61]
	v_mfma_f32_16x16x32_bf16 v[58:61], v[134:137], v[204:207], v[58:61]
	v_mfma_f32_16x16x32_bf16 v[50:53], v[150:153], v[180:183], v[50:53]
	v_mfma_f32_16x16x32_bf16 v[50:53], v[154:157], v[184:187], v[50:53]
	v_mfma_f32_16x16x32_bf16 v[46:49], v[172:175], v[184:187], v[46:49]
	v_mfma_f32_16x16x32_bf16 v[46:49], v[158:161], v[180:183], v[46:49]
	v_mfma_f32_16x16x32_bf16 v[38:41], v[158:161], v[188:191], v[38:41]
	v_mfma_f32_16x16x32_bf16 v[38:41], v[172:175], v[192:195], v[38:41]
	v_mfma_f32_16x16x32_bf16 v[42:45], v[154:157], v[192:195], v[42:45]
	v_mfma_f32_16x16x32_bf16 v[42:45], v[150:153], v[188:191], v[42:45]
	v_mfma_f32_16x16x32_bf16 v[34:37], v[150:153], v[196:199], v[34:37]
	v_mfma_f32_16x16x32_bf16 v[34:37], v[154:157], v[200:203], v[34:37]
	v_mfma_f32_16x16x32_bf16 v[28:31], v[172:175], v[200:203], v[28:31]
	v_mfma_f32_16x16x32_bf16 v[28:31], v[158:161], v[196:199], v[28:31]
	v_mfma_f32_16x16x32_bf16 v[20:23], v[158:161], v[204:207], v[20:23]
	v_mfma_f32_16x16x32_bf16 v[20:23], v[172:175], v[208:211], v[20:23]
	v_mfma_f32_16x16x32_bf16 v[24:27], v[154:157], v[208:211], v[24:27]
	v_mfma_f32_16x16x32_bf16 v[24:27], v[150:153], v[204:207], v[24:27]
	s_setprio 0
	s_barrier
	s_add_i32 s54, s56, s13
	v_lshl_add_u64 v[212:213], s[38:39], 0, v[32:33]
	s_mov_b32 m0, s54
	ds_read_b128 v[180:183], v179 offset:16384
	ds_read_b128 v[184:187], v179 offset:17408
	ds_read_b128 v[188:191], v179 offset:18432
	ds_read_b128 v[192:195], v179 offset:19456
	ds_read_b128 v[196:199], v179 offset:20480
	ds_read_b128 v[200:203], v179 offset:21504
	ds_read_b128 v[204:207], v179 offset:22528
	ds_read_b128 v[208:211], v179 offset:23552
	global_load_lds_dwordx4 v[212:213], off
	s_add_i32 m0, s54, 0x2000
	s_add_u32 s54, s38, 0x80000
	v_lshl_add_u64 v[214:215], s[38:39], 0, v[166:167]
	s_addc_u32 s55, s39, 0
	s_add_i32 s56, s57, s13
	global_load_lds_dwordx4 v[214:215], off
	s_mov_b32 m0, s56
	v_lshl_add_u64 v[220:221], s[40:41], 0, v[164:165]
	global_load_lds_dwordx4 v32, s[54:55]
	s_add_i32 m0, s56, 0x2000
	s_nop 0
	global_load_lds_dwordx4 v166, s[54:55]
	v_lshl_add_u64 v[216:217], s[40:41], 0, v[162:163]
	s_mov_b32 m0, s24
	s_nop 0
	global_load_lds_dwordx4 v[216:217], off
	s_mov_b32 m0, s25
	s_nop 0
	global_load_lds_dwordx4 v[220:221], off
	s_waitcnt vmcnt(8)
	s_waitcnt lgkmcnt(0)
	s_barrier
	s_setprio 1
	v_mfma_f32_16x16x32_bf16 v[16:19], v[134:137], v[180:183], v[16:19]
	v_mfma_f32_16x16x32_bf16 v[16:19], v[138:141], v[184:187], v[16:19]
	v_mfma_f32_16x16x32_bf16 v[12:15], v[146:149], v[184:187], v[12:15]
	v_mfma_f32_16x16x32_bf16 v[12:15], v[142:145], v[180:183], v[12:15]
	v_mfma_f32_16x16x32_bf16 v[4:7], v[142:145], v[188:191], v[4:7]
	v_mfma_f32_16x16x32_bf16 v[4:7], v[146:149], v[192:195], v[4:7]
	v_mfma_f32_16x16x32_bf16 v[8:11], v[138:141], v[192:195], v[8:11]
	v_mfma_f32_16x16x32_bf16 v[8:11], v[134:137], v[188:191], v[8:11]
	v_mfma_f32_16x16x32_bf16 v[0:3], v[134:137], v[196:199], v[0:3]
	v_mfma_f32_16x16x32_bf16 v[0:3], v[138:141], v[200:203], v[0:3]
	v_mfma_f32_16x16x32_bf16 v[86:89], v[146:149], v[200:203], v[86:89]
	v_mfma_f32_16x16x32_bf16 v[86:89], v[142:145], v[196:199], v[86:89]
	v_mfma_f32_16x16x32_bf16 v[94:97], v[142:145], v[204:207], v[94:97]
	v_mfma_f32_16x16x32_bf16 v[94:97], v[146:149], v[208:211], v[94:97]
	v_mfma_f32_16x16x32_bf16 v[90:93], v[138:141], v[208:211], v[90:93]
	v_mfma_f32_16x16x32_bf16 v[90:93], v[134:137], v[204:207], v[90:93]
	v_mfma_f32_16x16x32_bf16 v[98:101], v[150:153], v[180:183], v[98:101]
	v_mfma_f32_16x16x32_bf16 v[98:101], v[154:157], v[184:187], v[98:101]
	v_mfma_f32_16x16x32_bf16 v[102:105], v[172:175], v[184:187], v[102:105]
	v_mfma_f32_16x16x32_bf16 v[102:105], v[158:161], v[180:183], v[102:105]
	v_mfma_f32_16x16x32_bf16 v[110:113], v[158:161], v[188:191], v[110:113]
	v_mfma_f32_16x16x32_bf16 v[110:113], v[172:175], v[192:195], v[110:113]
	v_mfma_f32_16x16x32_bf16 v[106:109], v[154:157], v[192:195], v[106:109]
	v_mfma_f32_16x16x32_bf16 v[106:109], v[150:153], v[188:191], v[106:109]
	v_mfma_f32_16x16x32_bf16 v[114:117], v[150:153], v[196:199], v[114:117]
	v_mfma_f32_16x16x32_bf16 v[114:117], v[154:157], v[200:203], v[114:117]
	v_mfma_f32_16x16x32_bf16 v[118:121], v[172:175], v[200:203], v[118:121]
	v_mfma_f32_16x16x32_bf16 v[118:121], v[158:161], v[196:199], v[118:121]
	v_mfma_f32_16x16x32_bf16 v[126:129], v[158:161], v[204:207], v[126:129]
	v_mfma_f32_16x16x32_bf16 v[126:129], v[172:175], v[208:211], v[126:129]
	v_mfma_f32_16x16x32_bf16 v[122:125], v[154:157], v[208:211], v[122:125]
	v_mfma_f32_16x16x32_bf16 v[122:125], v[150:153], v[204:207], v[122:125]
	s_setprio 0
	s_barrier
	s_add_i32 s54, 0, 0x18000
	s_add_i32 s55, 0, 0x1c000
	v_add_u32_e32 v146, s54, v178
	v_add_u32_e32 v172, s55, v178
	ds_read_b128 v[134:137], v146
	ds_read_b128 v[138:141], v146 offset:1024
	ds_read_b128 v[142:145], v146 offset:2048
	ds_read_b128 v[146:149], v146 offset:3072
	ds_read_b128 v[150:153], v172
	ds_read_b128 v[154:157], v172 offset:1024
	ds_read_b128 v[158:161], v172 offset:2048
	ds_read_b128 v[172:175], v172 offset:3072
	s_add_u32 s40, s40, 0x80000
	s_addc_u32 s41, s41, 0
	s_mov_b32 m0, s33
	ds_read_b128 v[180:183], v179 offset:32768
	ds_read_b128 v[184:187], v179 offset:33792
	ds_read_b128 v[188:191], v179 offset:34816
	ds_read_b128 v[192:195], v179 offset:35840
	ds_read_b128 v[196:199], v179 offset:36864
	ds_read_b128 v[200:203], v179 offset:37888
	ds_read_b128 v[204:207], v179 offset:38912
	ds_read_b128 v[208:211], v179 offset:39936
	global_load_lds_dwordx4 v162, s[40:41]
	s_mov_b32 m0, s36
	s_nop 0
	global_load_lds_dwordx4 v164, s[40:41]
	s_waitcnt vmcnt(8)
	s_waitcnt lgkmcnt(0)
	s_barrier
	s_setprio 1
	v_mfma_f32_16x16x32_bf16 v[82:85], v[134:137], v[180:183], v[82:85]
	v_mfma_f32_16x16x32_bf16 v[82:85], v[138:141], v[184:187], v[82:85]
	v_mfma_f32_16x16x32_bf16 v[78:81], v[146:149], v[184:187], v[78:81]
	v_mfma_f32_16x16x32_bf16 v[78:81], v[142:145], v[180:183], v[78:81]
	v_mfma_f32_16x16x32_bf16 v[70:73], v[142:145], v[188:191], v[70:73]
	v_mfma_f32_16x16x32_bf16 v[70:73], v[146:149], v[192:195], v[70:73]
	v_mfma_f32_16x16x32_bf16 v[74:77], v[138:141], v[192:195], v[74:77]
	v_mfma_f32_16x16x32_bf16 v[74:77], v[134:137], v[188:191], v[74:77]
	v_mfma_f32_16x16x32_bf16 v[66:69], v[134:137], v[196:199], v[66:69]
	v_mfma_f32_16x16x32_bf16 v[66:69], v[138:141], v[200:203], v[66:69]
	v_mfma_f32_16x16x32_bf16 v[62:65], v[146:149], v[200:203], v[62:65]
	v_mfma_f32_16x16x32_bf16 v[62:65], v[142:145], v[196:199], v[62:65]
	v_mfma_f32_16x16x32_bf16 v[54:57], v[142:145], v[204:207], v[54:57]
	v_mfma_f32_16x16x32_bf16 v[54:57], v[146:149], v[208:211], v[54:57]
	v_mfma_f32_16x16x32_bf16 v[58:61], v[138:141], v[208:211], v[58:61]
	v_mfma_f32_16x16x32_bf16 v[58:61], v[134:137], v[204:207], v[58:61]
	v_mfma_f32_16x16x32_bf16 v[50:53], v[150:153], v[180:183], v[50:53]
	v_mfma_f32_16x16x32_bf16 v[50:53], v[154:157], v[184:187], v[50:53]
	v_mfma_f32_16x16x32_bf16 v[46:49], v[172:175], v[184:187], v[46:49]
	v_mfma_f32_16x16x32_bf16 v[46:49], v[158:161], v[180:183], v[46:49]
	v_mfma_f32_16x16x32_bf16 v[38:41], v[158:161], v[188:191], v[38:41]
	v_mfma_f32_16x16x32_bf16 v[38:41], v[172:175], v[192:195], v[38:41]
	v_mfma_f32_16x16x32_bf16 v[42:45], v[154:157], v[192:195], v[42:45]
	v_mfma_f32_16x16x32_bf16 v[42:45], v[150:153], v[188:191], v[42:45]
	v_mfma_f32_16x16x32_bf16 v[34:37], v[150:153], v[196:199], v[34:37]
	v_mfma_f32_16x16x32_bf16 v[34:37], v[154:157], v[200:203], v[34:37]
	v_mfma_f32_16x16x32_bf16 v[28:31], v[172:175], v[200:203], v[28:31]
	v_mfma_f32_16x16x32_bf16 v[28:31], v[158:161], v[196:199], v[28:31]
	v_mfma_f32_16x16x32_bf16 v[20:23], v[158:161], v[204:207], v[20:23]
	v_mfma_f32_16x16x32_bf16 v[20:23], v[172:175], v[208:211], v[20:23]
	v_mfma_f32_16x16x32_bf16 v[24:27], v[154:157], v[208:211], v[24:27]
	v_mfma_f32_16x16x32_bf16 v[24:27], v[150:153], v[204:207], v[24:27]
	s_setprio 0
	s_barrier
	s_add_i32 s40, s54, s13
	v_lshl_add_u64 v[212:213], v[212:213], 0, s[34:35]
	s_mov_b32 m0, s40
	ds_read_b128 v[180:183], v179 offset:49152
	ds_read_b128 v[184:187], v179 offset:50176
	ds_read_b128 v[188:191], v179 offset:51200
	ds_read_b128 v[192:195], v179 offset:52224
	ds_read_b128 v[196:199], v179 offset:53248
	ds_read_b128 v[200:203], v179 offset:54272
	ds_read_b128 v[204:207], v179 offset:55296
	ds_read_b128 v[208:211], v179 offset:56320
	global_load_lds_dwordx4 v[212:213], off
	s_add_i32 m0, s40, 0x2000
	s_add_u32 s38, s38, 0x80080
	v_lshl_add_u64 v[212:213], v[214:215], 0, s[34:35]
	s_addc_u32 s39, s39, 0
	s_add_i32 s40, s55, s13
	global_load_lds_dwordx4 v[212:213], off
	s_mov_b32 m0, s40
	s_nop 0
	global_load_lds_dwordx4 v32, s[38:39]
	s_add_i32 m0, s40, 0x2000
	s_nop 0
	global_load_lds_dwordx4 v166, s[38:39]
	v_lshl_add_u64 v[212:213], v[216:217], 0, s[34:35]
	s_mov_b32 m0, s43
	s_nop 0
	global_load_lds_dwordx4 v[212:213], off
	v_lshl_add_u64 v[212:213], v[220:221], 0, s[34:35]
	s_mov_b32 m0, s44
	s_nop 0
	global_load_lds_dwordx4 v[212:213], off
	s_waitcnt vmcnt(8)
	s_waitcnt lgkmcnt(0)
	s_barrier
	s_setprio 1
	v_mfma_f32_16x16x32_bf16 v[16:19], v[134:137], v[180:183], v[16:19]
	v_mfma_f32_16x16x32_bf16 v[16:19], v[138:141], v[184:187], v[16:19]
	v_mfma_f32_16x16x32_bf16 v[12:15], v[146:149], v[184:187], v[12:15]
	v_mfma_f32_16x16x32_bf16 v[12:15], v[142:145], v[180:183], v[12:15]
	v_mfma_f32_16x16x32_bf16 v[4:7], v[142:145], v[188:191], v[4:7]
	v_mfma_f32_16x16x32_bf16 v[4:7], v[146:149], v[192:195], v[4:7]
	v_mfma_f32_16x16x32_bf16 v[8:11], v[138:141], v[192:195], v[8:11]
	v_mfma_f32_16x16x32_bf16 v[8:11], v[134:137], v[188:191], v[8:11]
	v_mfma_f32_16x16x32_bf16 v[0:3], v[134:137], v[196:199], v[0:3]
	v_mfma_f32_16x16x32_bf16 v[0:3], v[138:141], v[200:203], v[0:3]
	v_mfma_f32_16x16x32_bf16 v[86:89], v[146:149], v[200:203], v[86:89]
	v_mfma_f32_16x16x32_bf16 v[86:89], v[142:145], v[196:199], v[86:89]
	v_mfma_f32_16x16x32_bf16 v[94:97], v[142:145], v[204:207], v[94:97]
	v_mfma_f32_16x16x32_bf16 v[94:97], v[146:149], v[208:211], v[94:97]
	v_mfma_f32_16x16x32_bf16 v[90:93], v[138:141], v[208:211], v[90:93]
	v_mfma_f32_16x16x32_bf16 v[90:93], v[134:137], v[204:207], v[90:93]
	v_mfma_f32_16x16x32_bf16 v[98:101], v[150:153], v[180:183], v[98:101]
	v_mfma_f32_16x16x32_bf16 v[98:101], v[154:157], v[184:187], v[98:101]
	v_mfma_f32_16x16x32_bf16 v[102:105], v[172:175], v[184:187], v[102:105]
	v_mfma_f32_16x16x32_bf16 v[102:105], v[158:161], v[180:183], v[102:105]
	v_mfma_f32_16x16x32_bf16 v[110:113], v[158:161], v[188:191], v[110:113]
	v_mfma_f32_16x16x32_bf16 v[110:113], v[172:175], v[192:195], v[110:113]
	v_mfma_f32_16x16x32_bf16 v[106:109], v[154:157], v[192:195], v[106:109]
	v_mfma_f32_16x16x32_bf16 v[106:109], v[150:153], v[188:191], v[106:109]
	v_mfma_f32_16x16x32_bf16 v[114:117], v[150:153], v[196:199], v[114:117]
	v_mfma_f32_16x16x32_bf16 v[114:117], v[154:157], v[200:203], v[114:117]
	v_mfma_f32_16x16x32_bf16 v[118:121], v[172:175], v[200:203], v[118:121]
	v_mfma_f32_16x16x32_bf16 v[118:121], v[158:161], v[196:199], v[118:121]
	v_mfma_f32_16x16x32_bf16 v[126:129], v[158:161], v[204:207], v[126:129]
	v_mfma_f32_16x16x32_bf16 v[126:129], v[172:175], v[208:211], v[126:129]
	v_mfma_f32_16x16x32_bf16 v[122:125], v[154:157], v[208:211], v[122:125]
	v_mfma_f32_16x16x32_bf16 v[122:125], v[150:153], v[204:207], v[122:125]
	s_setprio 0
	s_barrier
	s_add_i32 s53, s53, 2
	s_add_u32 s30, s30, 0x100
	s_addc_u32 s31, s31, 0
	s_cmp_gt_u32 s53, 29
	s_cbranch_scc0 .LBB0_888
	s_and_b64 vcc, exec, s[18:19]
	s_cbranch_vccz .LBB0_891
	s_barrier
